# v23 + nt on the final out stores of the P10 epilogue (never re-read by the kernel)
# baseline (speedup 1.0000x reference)
;     __device__ __forceinline__ void operator()(const f32x4 (&acc)[2][2][4][2], const Unit& u, int wr, int wc, int fr, int fq) const {
;         const int row0 = u.pm * 256 + wr * 64 + fr; const int col0 = u.pn * 256 + wc * 32 + 4 * fq;
;         const float* gp = gate + (size_t)(u.pm / 16) * ADAW;
; #pragma unroll
;         for (int bj = 0; bj < 2; ++bj)
; #pragma unroll
;             for (int n = 0; n < 2; ++n) {
;                 const int col = col0 + bj * HALF + n * 16;
;                 const f32x4 g = *(const f32x4*)(gp + col);
; #pragma unroll
;                 for (int ai = 0; ai < 2; ++ai)
; #pragma unroll
;                     for (int m = 0; m < 4; ++m) {
;                         const size_t off = (size_t)(row0 + ai * HALF + m * 16) * D + col;
;                         *(f32x4*)(out + off) = *(const f32x4*)(base + off) + g * acc[ai][bj][m][n];
;                     }
;             }
.LBB0_914:
	v_lshl_add_u32 v210, s49, 8, v218
	v_lshl_add_u32 v212, s50, 8, v220
	v_mov_b32_e32 v211, 0
	v_mov_b32_e32 v213, 0
	v_lshlrev_b64 v[210:211], 12, v[210:211]
	v_lshlrev_b32_e32 v212, 2, v212
	s_lshr_b32 s18, s49, 4
	s_mul_i32 s18, s18, 0x6000
	s_add_u32 s18, s28, s18
	s_addc_u32 s19, s29, 0
	v_lshl_add_u64 v[192:193], s[26:27], 0, v[210:211]
	v_lshl_add_u64 v[208:209], s[18:19], 0, v[212:213]
	v_lshl_add_u64 v[192:193], v[192:193], 0, v[212:213]
	global_load_dwordx4 v[224:227], v[208:209], off
	global_load_dwordx4 v[228:231], v[208:209], off offset:64
	global_load_dwordx4 v[232:235], v[208:209], off offset:512
	global_load_dwordx4 v[236:239], v[208:209], off offset:576
	global_load_dwordx4 v[128:131], v[192:193], off nt
	global_load_dwordx4 v[132:135], v[192:193], off offset:64 nt
	global_load_dwordx4 v[136:139], v[192:193], off offset:512 nt
	global_load_dwordx4 v[140:143], v[192:193], off offset:576 nt
	s_mov_b64 s[18:19], 0x10000
	v_lshl_add_u64 v[194:195], v[192:193], 0, s[18:19]
	global_load_dwordx4 v[144:147], v[194:195], off nt
	global_load_dwordx4 v[148:151], v[194:195], off offset:64 nt
	global_load_dwordx4 v[152:155], v[194:195], off offset:512 nt
	global_load_dwordx4 v[156:159], v[194:195], off offset:576 nt
	s_mov_b64 s[18:19], 0x20000
	v_lshl_add_u64 v[196:197], v[192:193], 0, s[18:19]
	global_load_dwordx4 v[160:163], v[196:197], off nt
	global_load_dwordx4 v[164:167], v[196:197], off offset:64 nt
	global_load_dwordx4 v[168:171], v[196:197], off offset:512 nt
	global_load_dwordx4 v[172:175], v[196:197], off offset:576 nt
	s_mov_b64 s[18:19], 0x30000
	v_lshl_add_u64 v[198:199], v[192:193], 0, s[18:19]
	v_lshl_add_u64 v[200:201], v[192:193], 0, s[10:11]
	v_lshl_add_u64 v[202:203], v[192:193], 0, s[12:13]
	v_lshl_add_u64 v[204:205], v[192:193], 0, s[14:15]
	v_lshl_add_u64 v[206:207], v[192:193], 0, s[6:7]
	s_waitcnt vmcnt(8)
	v_pk_fma_f32 v[124:125], v[124:125], v[224:225], v[128:129]
	v_pk_fma_f32 v[126:127], v[126:127], v[226:227], v[130:131]
	v_pk_fma_f32 v[108:109], v[108:109], v[228:229], v[132:133]
	v_pk_fma_f32 v[110:111], v[110:111], v[230:231], v[134:135]
	v_pk_fma_f32 v[80:81], v[80:81], v[232:233], v[136:137]
	v_pk_fma_f32 v[82:83], v[82:83], v[234:235], v[138:139]
	v_pk_fma_f32 v[48:49], v[48:49], v[236:237], v[140:141]
	v_pk_fma_f32 v[50:51], v[50:51], v[238:239], v[142:143]
	global_store_dwordx4 v[192:193], v[124:127], off nt
	global_store_dwordx4 v[192:193], v[108:111], off offset:64 nt
	global_store_dwordx4 v[192:193], v[80:83], off offset:512 nt
	global_store_dwordx4 v[192:193], v[48:51], off offset:576 nt
	global_load_dwordx4 v[128:131], v[198:199], off nt
	global_load_dwordx4 v[132:135], v[198:199], off offset:64 nt
	global_load_dwordx4 v[136:139], v[198:199], off offset:512 nt
	global_load_dwordx4 v[140:143], v[198:199], off offset:576 nt
	s_waitcnt vmcnt(12)
	v_pk_fma_f32 v[120:121], v[120:121], v[224:225], v[144:145]
	v_pk_fma_f32 v[122:123], v[122:123], v[226:227], v[146:147]
	v_pk_fma_f32 v[104:105], v[104:105], v[228:229], v[148:149]
	v_pk_fma_f32 v[106:107], v[106:107], v[230:231], v[150:151]
	v_pk_fma_f32 v[76:77], v[76:77], v[232:233], v[152:153]
	v_pk_fma_f32 v[78:79], v[78:79], v[234:235], v[154:155]
	v_pk_fma_f32 v[40:41], v[40:41], v[236:237], v[156:157]
	v_pk_fma_f32 v[42:43], v[42:43], v[238:239], v[158:159]
	global_store_dwordx4 v[194:195], v[120:123], off nt
	global_store_dwordx4 v[194:195], v[104:107], off offset:64 nt
	global_store_dwordx4 v[194:195], v[76:79], off offset:512 nt
	global_store_dwordx4 v[194:195], v[40:43], off offset:576 nt
	global_load_dwordx4 v[144:147], v[200:201], off nt
	global_load_dwordx4 v[148:151], v[200:201], off offset:64 nt
	global_load_dwordx4 v[152:155], v[200:201], off offset:512 nt
	global_load_dwordx4 v[156:159], v[200:201], off offset:576 nt
	s_waitcnt vmcnt(16)
	v_pk_fma_f32 v[116:117], v[116:117], v[224:225], v[160:161]
	v_pk_fma_f32 v[118:119], v[118:119], v[226:227], v[162:163]
	v_pk_fma_f32 v[100:101], v[100:101], v[228:229], v[164:165]
	v_pk_fma_f32 v[102:103], v[102:103], v[230:231], v[166:167]
	v_pk_fma_f32 v[64:65], v[64:65], v[232:233], v[168:169]
	v_pk_fma_f32 v[66:67], v[66:67], v[234:235], v[170:171]
	v_pk_fma_f32 v[36:37], v[36:37], v[236:237], v[172:173]
	v_pk_fma_f32 v[38:39], v[38:39], v[238:239], v[174:175]
	global_store_dwordx4 v[196:197], v[116:119], off nt
	global_store_dwordx4 v[196:197], v[100:103], off offset:64 nt
	global_store_dwordx4 v[196:197], v[64:67], off offset:512 nt
	global_store_dwordx4 v[196:197], v[36:39], off offset:576 nt
	global_load_dwordx4 v[160:163], v[202:203], off nt
	global_load_dwordx4 v[164:167], v[202:203], off offset:64 nt
	global_load_dwordx4 v[168:171], v[202:203], off offset:512 nt
	global_load_dwordx4 v[172:175], v[202:203], off offset:576 nt
	s_waitcnt vmcnt(16)
;     __device__ __forceinline__ void operator()(const f32x4 (&acc)[2][2][4][2], const Unit& u, int wr, int wc, int fr, int fq) const {
;     ...
;         for (int bj = 0; bj < 2; ++bj)
; #pragma unroll
;             for (int n = 0; n < 2; ++n) {
;                 const int col = col0 + bj * HALF + n * 16;
;                 const f32x4 g = *(const f32x4*)(gp + col);
; #pragma unroll
;                 for (int ai = 0; ai < 2; ++ai)
; #pragma unroll
;                     for (int m = 0; m < 4; ++m) {
;                         const size_t off = (size_t)(row0 + ai * HALF + m * 16) * D + col;
;                         *(f32x4*)(out + off) = *(const f32x4*)(base + off) + g * acc[ai][bj][m][n];
;                     }
;             }
	v_pk_fma_f32 v[112:113], v[112:113], v[224:225], v[128:129]
	v_pk_fma_f32 v[114:115], v[114:115], v[226:227], v[130:131]
	v_pk_fma_f32 v[96:97], v[96:97], v[228:229], v[132:133]
	v_pk_fma_f32 v[98:99], v[98:99], v[230:231], v[134:135]
	v_pk_fma_f32 v[56:57], v[56:57], v[232:233], v[136:137]
	v_pk_fma_f32 v[58:59], v[58:59], v[234:235], v[138:139]
	v_pk_fma_f32 v[32:33], v[32:33], v[236:237], v[140:141]
	v_pk_fma_f32 v[34:35], v[34:35], v[238:239], v[142:143]
	global_store_dwordx4 v[198:199], v[112:115], off nt
	global_store_dwordx4 v[198:199], v[96:99], off offset:64 nt
	global_store_dwordx4 v[198:199], v[56:59], off offset:512 nt
	global_store_dwordx4 v[198:199], v[32:35], off offset:576 nt
	global_load_dwordx4 v[128:131], v[204:205], off nt
	global_load_dwordx4 v[132:135], v[204:205], off offset:64 nt
	global_load_dwordx4 v[136:139], v[204:205], off offset:512 nt
	global_load_dwordx4 v[140:143], v[204:205], off offset:576 nt
	s_waitcnt vmcnt(16)
	v_pk_fma_f32 v[92:93], v[92:93], v[224:225], v[144:145]
	v_pk_fma_f32 v[94:95], v[94:95], v[226:227], v[146:147]
	v_pk_fma_f32 v[68:69], v[68:69], v[228:229], v[148:149]
	v_pk_fma_f32 v[70:71], v[70:71], v[230:231], v[150:151]
	v_pk_fma_f32 v[28:29], v[28:29], v[232:233], v[152:153]
	v_pk_fma_f32 v[30:31], v[30:31], v[234:235], v[154:155]
	v_pk_fma_f32 v[12:13], v[12:13], v[236:237], v[156:157]
	v_pk_fma_f32 v[14:15], v[14:15], v[238:239], v[158:159]
	global_store_dwordx4 v[200:201], v[92:95], off nt
	global_store_dwordx4 v[200:201], v[68:71], off offset:64 nt
	global_store_dwordx4 v[200:201], v[28:31], off offset:512 nt
	global_store_dwordx4 v[200:201], v[12:15], off offset:576 nt
	global_load_dwordx4 v[144:147], v[206:207], off nt
	global_load_dwordx4 v[148:151], v[206:207], off offset:64 nt
	global_load_dwordx4 v[152:155], v[206:207], off offset:512 nt
	global_load_dwordx4 v[156:159], v[206:207], off offset:576 nt
	s_waitcnt vmcnt(16)
	v_pk_fma_f32 v[88:89], v[88:89], v[224:225], v[160:161]
	v_pk_fma_f32 v[90:91], v[90:91], v[226:227], v[162:163]
	v_pk_fma_f32 v[60:61], v[60:61], v[228:229], v[164:165]
	v_pk_fma_f32 v[62:63], v[62:63], v[230:231], v[166:167]
	v_pk_fma_f32 v[24:25], v[24:25], v[232:233], v[168:169]
	v_pk_fma_f32 v[26:27], v[26:27], v[234:235], v[170:171]
	v_pk_fma_f32 v[8:9], v[8:9], v[236:237], v[172:173]
	v_pk_fma_f32 v[10:11], v[10:11], v[238:239], v[174:175]
	global_store_dwordx4 v[202:203], v[88:91], off nt
	global_store_dwordx4 v[202:203], v[60:63], off offset:64 nt
	global_store_dwordx4 v[202:203], v[24:27], off offset:512 nt
	global_store_dwordx4 v[202:203], v[8:11], off offset:576 nt
	s_waitcnt vmcnt(12)
	v_pk_fma_f32 v[84:85], v[84:85], v[224:225], v[128:129]
	v_pk_fma_f32 v[86:87], v[86:87], v[226:227], v[130:131]
	v_pk_fma_f32 v[52:53], v[52:53], v[228:229], v[132:133]
	v_pk_fma_f32 v[54:55], v[54:55], v[230:231], v[134:135]
	v_pk_fma_f32 v[20:21], v[20:21], v[232:233], v[136:137]
	v_pk_fma_f32 v[22:23], v[22:23], v[234:235], v[138:139]
	v_pk_fma_f32 v[4:5], v[4:5], v[236:237], v[140:141]
	v_pk_fma_f32 v[6:7], v[6:7], v[238:239], v[142:143]
	global_store_dwordx4 v[204:205], v[84:87], off nt
	global_store_dwordx4 v[204:205], v[52:55], off offset:64 nt
	global_store_dwordx4 v[204:205], v[20:23], off offset:512 nt
	global_store_dwordx4 v[204:205], v[4:7], off offset:576 nt
	s_waitcnt vmcnt(8)
	v_pk_fma_f32 v[72:73], v[72:73], v[224:225], v[144:145]
	v_pk_fma_f32 v[74:75], v[74:75], v[226:227], v[146:147]
	v_pk_fma_f32 v[44:45], v[44:45], v[228:229], v[148:149]
	v_pk_fma_f32 v[46:47], v[46:47], v[230:231], v[150:151]
	v_pk_fma_f32 v[16:17], v[16:17], v[232:233], v[152:153]
	v_pk_fma_f32 v[18:19], v[18:19], v[234:235], v[154:155]
	v_pk_fma_f32 v[0:1], v[0:1], v[236:237], v[156:157]
	v_pk_fma_f32 v[2:3], v[2:3], v[238:239], v[158:159]
	global_store_dwordx4 v[206:207], v[72:75], off nt
	global_store_dwordx4 v[206:207], v[44:47], off offset:64 nt
	global_store_dwordx4 v[206:207], v[16:19], off offset:512 nt
	global_store_dwordx4 v[206:207], v[0:3], off offset:576 nt
	s_and_b64 vcc, exec, s[0:1]
	s_mov_b64 s[0:1], -1
	s_cbranch_vccnz .LBB0_899
	s_and_b64 vcc, exec, s[62:63]
	s_cbranch_vccnz .LBB0_898
	s_barrier
	s_branch .LBB0_898
